# attn_prep: 16 v-row loads per job issued together with one wait (were 8 serial wait-for-all pairs); gate_pass: gain-vector copies moved behind all z loads
# speedup vs baseline: 1.0046x; 1.0046x over previous
; #define GAS __attribute__((address_space(1)))
; DI unsigned pk2(float lo, float hi) { f32x2 v = {lo, hi}; bf16x2_t b = __builtin_convertvector(v, bf16x2_t); return __builtin_bit_cast(unsigned, b); }
; DI float bflo(unsigned w) { return __uint_as_float(w << 16); }
; DI float bfhi(unsigned w) { return __uint_as_float(w & 0xffff0000u); }
; DI void attn_prep_job(const Frame& F, int job) {
;     ...
;         const int kk = tid >> 3, c = (tid >> 2) & 1, dg = tid & 3, t = tile * 64 + kk; const size_t m = (size_t)b * SEQ + t;
;         float cs[8], sn[8];
; #pragma unroll
;         for (int i = 0; i < 8; ++i) { const f32x2 v = rope[t * 32 + 8 * dg + i]; cs[i] = v.x; sn[i] = v.y; }
;         v4u la[2], lb[2];
; #pragma unroll
;         for (int isk = 0; isk < 2; ++isk) { const bf16* src = P + m * NP + (isk ? PA_K : PA_Q) + h * 128 + c * 64 + 8 * dg; la[isk] = *(const GAS v4u*)src; lb[isk] = *(const GAS v4u*)(src + 32); }
; #pragma unroll
;         for (int isk = 0; isk < 2; ++isk) {
;             const v4u a = la[isk], bb = lb[isk];
;             float x1[8], x2[8];
;             x1[0] = bflo(a.x); x1[1] = bfhi(a.x); x1[2] = bflo(a.y); x1[3] = bfhi(a.y); x1[4] = bflo(a.z); x1[5] = bfhi(a.z); x1[6] = bflo(a.w); x1[7] = bfhi(a.w);
;             x2[0] = bflo(bb.x); x2[1] = bfhi(bb.x); x2[2] = bflo(bb.y); x2[3] = bfhi(bb.y); x2[4] = bflo(bb.z); x2[5] = bfhi(bb.z); x2[6] = bflo(bb.w); x2[7] = bfhi(bb.w);
;             const float sc = isk ? 1.0f : 0.125f * 1.4426950408889634f;
;             float o1[8], o2[8];
; #pragma unroll
;             for (int i = 0; i < 8; ++i) { o1[i] = (x1[i] * cs[i] - x2[i] * sn[i]) * sc; o2[i] = (x2[i] * cs[i] + x1[i] * sn[i]) * sc; }
;             v4u w1, w2; w1.x = pk2(o1[0], o1[1]); w1.y = pk2(o1[2], o1[3]); w1.z = pk2(o1[4], o1[5]); w1.w = pk2(o1[6], o1[7]);
;             w2.x = pk2(o2[0], o2[1]); w2.y = pk2(o2[2], o2[3]); w2.z = pk2(o2[4], o2[5]); w2.w = pk2(o2[6], o2[7]);
;             if (!isk) {
;                 bf16* q = (bf16*)(F.ws + WS_QR) + (((size_t)bh * 2 + c) * SEQ + t) * 64 + 8 * dg;
;                 *(GAS v4u*)q = w1; *(GAS v4u*)(q + 32) = w2;
.LBB0_814:
	s_and_b32 s46, s39, 63
	s_lshl_b32 s47, s46, 6
	v_add_u32_e32 v6, s47, v11
	s_ashr_i32 s42, s39, 8
	v_lshl_or_b32 v0, v6, 5, v8
	s_ashr_i32 s43, s42, 31
	v_ashrrev_i32_e32 v1, 31, v0
	v_ashrrev_i32_e32 v7, 31, v6
	v_lshl_add_u64 v[4:5], v[0:1], 3, s[34:35]
	s_lshl_b64 s[42:43], s[42:43], 12
	flat_load_dwordx4 v[0:3], v[4:5]
	flat_load_dwordx4 v[28:31], v[4:5] offset:16
	flat_load_dwordx4 v[32:35], v[4:5] offset:32
	flat_load_dwordx4 v[36:39], v[4:5] offset:48
	s_ashr_i32 s44, s39, 6
	v_lshl_add_u64 v[40:41], s[42:43], 0, v[6:7]
	v_mov_b64_e32 v[4:5], s[40:41]
	v_mad_u64_u32 v[42:43], s[48:49], v40, s97, v[4:5]
	s_lshl_b32 s2, s44, 8
	v_mad_i32_i24 v43, v41, s97, v43
	s_and_b32 s2, s2, 0x300
	s_ashr_i32 s45, s44, 31
	v_lshl_add_u64 v[40:41], v[42:43], 0, s[2:3]
	v_lshlrev_b32_e32 v96, 1, v10
	s_lshl_b64 s[48:49], s[44:45], 7
	v_lshl_add_u64 v[40:41], v[40:41], 0, v[96:97]
	v_lshlrev_b32_e32 v96, 1, v8
	s_or_b32 s48, s48, s46
	v_lshl_add_u64 v[52:53], v[40:41], 0, v[96:97]
	v_mov_b32_e32 v49, s49
	v_or_b32_e32 v48, s48, v10
	global_load_dwordx4 v[40:43], v[52:53], off offset:1024
	global_load_dwordx4 v[44:47], v[52:53], off offset:1088
	v_lshlrev_b64 v[56:57], 13, v[48:49]
	global_load_dwordx4 v[48:51], v[52:53], off offset:64
	s_nop 0
	global_load_dwordx4 v[52:55], v[52:53], off
	s_lshl_b64 s[48:49], s[44:45], 13
	v_mov_b32_e32 v27, v97
	s_waitcnt vmcnt(0) lgkmcnt(0)
	v_mov_b32_e32 v63, v2
	v_mov_b32_e32 v2, v1
	v_mov_b32_e32 v62, v0
	v_mov_b32_e32 v67, v34
	v_mov_b32_e32 v34, v33
	v_mov_b32_e32 v66, v32
	v_mov_b32_e32 v71, v38
	v_mov_b32_e32 v38, v37
	v_mov_b32_e32 v70, v36
	v_lshlrev_b32_e32 v58, 16, v48
	v_lshlrev_b32_e32 v60, 16, v52
	v_and_b32_e32 v61, 0xffff0000, v52
	v_and_b32_e32 v59, 0xffff0000, v48
	v_pk_mul_f32 v[0:1], v[2:3], v[60:61]
	v_lshlrev_b32_e32 v52, 16, v53
	v_pk_fma_f32 v[0:1], v[62:63], v[58:59], v[0:1]
	v_pk_mul_f32 v[58:59], v[2:3], v[58:59]
	v_and_b32_e32 v53, 0xffff0000, v53
	v_pk_fma_f32 v[58:59], v[62:63], v[60:61], v[58:59] neg_lo:[0,0,1] neg_hi:[0,0,1]
	v_mov_b32_e32 v61, v30
	v_mov_b32_e32 v30, v29
	v_lshlrev_b32_e32 v48, 16, v49
	v_and_b32_e32 v49, 0xffff0000, v49
	v_mov_b32_e32 v60, v28
	v_pk_mul_f32 v[28:29], v[30:31], v[52:53]
	v_pk_mul_f32 v[0:1], v[0:1], s[54:55] op_sel_hi:[1,0]
	v_pk_fma_f32 v[28:29], v[60:61], v[48:49], v[28:29]
	v_pk_mul_f32 v[48:49], v[30:31], v[48:49]
	v_pk_mul_f32 v[58:59], v[58:59], s[54:55] op_sel_hi:[1,0]
	v_pk_fma_f32 v[48:49], v[60:61], v[52:53], v[48:49] neg_lo:[0,0,1] neg_hi:[0,0,1]
	v_lshlrev_b32_e32 v52, 16, v54
	v_and_b32_e32 v53, 0xffff0000, v54
	v_pk_mul_f32 v[64:65], v[48:49], s[54:55] op_sel_hi:[1,0]
	v_lshlrev_b32_e32 v48, 16, v50
	v_and_b32_e32 v49, 0xffff0000, v50
	v_pk_mul_f32 v[32:33], v[34:35], v[52:53]
	v_lshlrev_b32_e32 v50, 16, v55
	v_pk_fma_f32 v[32:33], v[66:67], v[48:49], v[32:33]
	v_pk_mul_f32 v[48:49], v[34:35], v[48:49]
	v_pk_mul_f32 v[28:29], v[28:29], s[54:55] op_sel_hi:[1,0]
	v_pk_fma_f32 v[48:49], v[66:67], v[52:53], v[48:49] neg_lo:[0,0,1] neg_hi:[0,0,1]
	v_pk_mul_f32 v[32:33], v[32:33], s[54:55] op_sel_hi:[1,0]
	v_pk_mul_f32 v[68:69], v[48:49], s[54:55] op_sel_hi:[1,0]
	v_lshlrev_b32_e32 v48, 16, v51
	v_and_b32_e32 v49, 0xffff0000, v51
	v_and_b32_e32 v51, 0xffff0000, v55
	v_pk_mul_f32 v[36:37], v[38:39], v[50:51]
	v_cvt_pk_bf16_f32 v52, v58, v59
	v_pk_fma_f32 v[36:37], v[70:71], v[48:49], v[36:37]
	v_pk_mul_f32 v[48:49], v[38:39], v[48:49]
	v_pk_mul_f32 v[36:37], v[36:37], s[54:55] op_sel_hi:[1,0]
	v_pk_fma_f32 v[48:49], v[70:71], v[50:51], v[48:49] neg_lo:[0,0,1] neg_hi:[0,0,1]
	v_cvt_pk_bf16_f32 v53, v64, v65
	v_pk_mul_f32 v[72:73], v[48:49], s[54:55] op_sel_hi:[1,0]
	v_cvt_pk_bf16_f32 v48, v0, v1
	v_mov_b32_e32 v1, s49
	v_or_b32_e32 v0, s48, v12
	v_lshl_add_u64 v[0:1], v[0:1], 0, v[6:7]
	v_lshlrev_b64 v[0:1], 7, v[0:1]
	v_cvt_pk_bf16_f32 v54, v68, v69
	v_cvt_pk_bf16_f32 v55, v72, v73
	v_lshl_add_u64 v[0:1], v[14:15], 0, v[0:1]
	v_lshlrev_b32_e32 v6, 16, v44
	v_and_b32_e32 v7, 0xffff0000, v44
	v_cvt_pk_bf16_f32 v49, v28, v29
	v_cvt_pk_bf16_f32 v50, v32, v33
	v_cvt_pk_bf16_f32 v51, v36, v37
	global_store_dwordx4 v[0:1], v[52:55], off
	global_store_dwordx4 v[0:1], v[48:51], off offset:64
	v_lshlrev_b32_e32 v28, 16, v40
	v_and_b32_e32 v29, 0xffff0000, v40
	v_pk_mul_f32 v[0:1], v[62:63], v[6:7]
	s_lshl_b64 s[48:49], s[44:45], 20
; #define GAS __attribute__((address_space(1)))
; DI void attn_prep_job(const Frame& F, int job) {
;     ...
;             } else {
;                 unsigned char* kf = F.ws + WS_KF + (((size_t)bh * 2 + c) * 64 + tile) * 8192;
;                 const int kvb = kk >> 5, r32 = kk & 31;
;                 const int d1 = 8 * dg, d2 = 32 + 8 * dg;
;                 *(GAS v4u*)(kf + ((kvb * 4 + (d1 >> 4)) * 64 + r32 + 32 * ((d1 >> 3) & 1)) * 16) = w1;
;                 *(GAS v4u*)(kf + ((kvb * 4 + (d2 >> 4)) * 64 + r32 + 32 * ((d2 >> 3) & 1)) * 16) = w2;
;             }
;         }
;     }
;     {
;         unsigned char* vf = F.ws + WS_VF + ((size_t)bh * 64 + tile) * 16384;
;         unsigned short ev[2][8];
; #pragma unroll
;         for (int rep = 0; rep < 2; ++rep) {
;             const int task = tid + 512 * rep, dv = task & 127, grp = task >> 7, kb = grp >> 2, s = (grp >> 1) & 1, hh = grp & 1;
;             const GAS bf16* src = (const GAS bf16*)(P + ((size_t)b * SEQ + tile * 64 + 32 * kb + 16 * s + 4 * hh) * NP + PA_V + h * 128 + dv);
; #pragma unroll
;             for (int j = 0; j < 8; ++j) ev[rep][j] = src[(size_t)(8 * (j >> 2) + (j & 3)) * NP];
;         }
; #pragma unroll
;         for (int rep = 0; rep < 2; ++rep) {
;             const int task = tid + 512 * rep, dv = task & 127, grp = task >> 7, kb = grp >> 2, s = (grp >> 1) & 1, hh = grp & 1;
;             const unsigned short* e = ev[rep];
;             v4u w; w.x = e[0] | ((unsigned)e[1] << 16); w.y = e[2] | ((unsigned)e[3] << 16); w.z = e[4] | ((unsigned)e[5] << 16); w.w = e[6] | ((unsigned)e[7] << 16);
;             *(GAS v4u*)(vf + ((((dv >> 5) * 2 + kb) * 2 + s) * 64 + (dv & 31) + 32 * hh) * 16) = w;
;         }
	v_pk_fma_f32 v[0:1], v[2:3], v[28:29], v[0:1]
	v_pk_mul_f32 v[2:3], v[2:3], v[6:7]
	v_lshlrev_b32_e32 v6, 16, v41
	v_pk_fma_f32 v[2:3], v[62:63], v[28:29], v[2:3] neg_lo:[0,0,1] neg_hi:[0,0,1]
	v_and_b32_e32 v7, 0xffff0000, v41
	v_cvt_pk_bf16_f32 v28, v2, v3
	v_lshlrev_b32_e32 v2, 16, v45
	v_and_b32_e32 v3, 0xffff0000, v45
	v_pk_mul_f32 v[32:33], v[60:61], v[2:3]
	v_pk_mul_f32 v[2:3], v[30:31], v[2:3]
	v_pk_fma_f32 v[32:33], v[30:31], v[6:7], v[32:33]
	v_pk_fma_f32 v[2:3], v[60:61], v[6:7], v[2:3] neg_lo:[0,0,1] neg_hi:[0,0,1]
	v_lshlrev_b32_e32 v6, 16, v46
	v_and_b32_e32 v7, 0xffff0000, v46
	v_cvt_pk_bf16_f32 v29, v2, v3
	v_lshlrev_b32_e32 v30, 16, v42
	v_and_b32_e32 v31, 0xffff0000, v42
	v_pk_mul_f32 v[2:3], v[66:67], v[6:7]
	v_pk_mul_f32 v[6:7], v[34:35], v[6:7]
	v_pk_fma_f32 v[2:3], v[34:35], v[30:31], v[2:3]
	v_pk_fma_f32 v[6:7], v[66:67], v[30:31], v[6:7] neg_lo:[0,0,1] neg_hi:[0,0,1]
	v_cvt_pk_bf16_f32 v0, v0, v1
	v_cvt_pk_bf16_f32 v30, v6, v7
	v_lshlrev_b32_e32 v6, 16, v47
	v_and_b32_e32 v7, 0xffff0000, v47
	v_cvt_pk_bf16_f32 v1, v32, v33
	v_lshlrev_b32_e32 v32, 16, v43
	v_and_b32_e32 v33, 0xffff0000, v43
	v_pk_mul_f32 v[34:35], v[70:71], v[6:7]
	v_pk_mul_f32 v[6:7], v[38:39], v[6:7]
	v_pk_fma_f32 v[34:35], v[38:39], v[32:33], v[34:35]
	v_pk_fma_f32 v[6:7], v[70:71], v[32:33], v[6:7] neg_lo:[0,0,1] neg_hi:[0,0,1]
	v_cvt_pk_bf16_f32 v2, v2, v3
	v_cvt_pk_bf16_f32 v31, v6, v7
	v_lshl_add_u64 v[6:7], v[16:17], 0, v[56:57]
	v_cvt_pk_bf16_f32 v3, v34, v35
	global_store_dwordx4 v[6:7], v[28:31], off
	global_store_dwordx4 v[6:7], v[0:3], off offset:2048
	v_mov_b32_e32 v7, s43
	s_lshl_b32 s44, s46, 14
	v_or_b32_e32 v0, s47, v13
	v_or_b32_e32 v6, s42, v0
	v_lshl_add_u64 v[0:1], v[6:7], 0, v[18:19]
	v_mad_u64_u32 v[2:3], s[42:43], v0, s97, v[4:5]
	v_mad_i32_i24 v3, v1, s97, v3
	v_lshl_add_u64 v[0:1], v[2:3], 0, s[2:3]
	v_lshl_add_u64 v[28:29], v[0:1], 0, v[26:27]
	v_lshl_add_u64 v[6:7], v[6:7], 0, v[20:21]
	v_mad_u64_u32 v[4:5], s[42:43], v6, s97, v[4:5]
	v_mad_i32_i24 v5, v7, s97, v5
	v_lshl_add_u64 v[4:5], v[4:5], 0, s[2:3]
	v_lshl_add_u64 v[30:31], v[4:5], 0, v[26:27]
	v_mov_b32_e32 v49, v97
	global_load_ushort v32, v[28:29], off offset:2048
	global_load_ushort v40, v[30:31], off offset:2048
	v_mov_b32_e32 v48, s4
	v_lshl_add_u64 v[0:1], v[28:29], 0, v[48:49]
	v_lshl_add_u64 v[2:3], v[30:31], 0, v[48:49]
	global_load_ushort v33, v[0:1], off offset:1024
	global_load_ushort v41, v[2:3], off offset:1024
	v_mov_b32_e32 v48, s88
	v_lshl_add_u64 v[0:1], v[28:29], 0, v[48:49]
	v_lshl_add_u64 v[2:3], v[30:31], 0, v[48:49]
	global_load_ushort v34, v[0:1], off
	global_load_ushort v42, v[2:3], off
	v_mov_b32_e32 v48, s15
	v_lshl_add_u64 v[0:1], v[28:29], 0, v[48:49]
	v_lshl_add_u64 v[2:3], v[30:31], 0, v[48:49]
	global_load_ushort v35, v[0:1], off offset:3072
	global_load_ushort v43, v[2:3], off offset:3072
	v_mov_b32_e32 v48, s89
	v_lshl_add_u64 v[0:1], v[28:29], 0, v[48:49]
	v_lshl_add_u64 v[2:3], v[30:31], 0, v[48:49]
	global_load_ushort v36, v[0:1], off offset:2048
	global_load_ushort v44, v[2:3], off offset:2048
	v_mov_b32_e32 v48, s16
	v_lshl_add_u64 v[0:1], v[28:29], 0, v[48:49]
	v_lshl_add_u64 v[2:3], v[30:31], 0, v[48:49]
	global_load_ushort v37, v[0:1], off offset:1024
	global_load_ushort v45, v[2:3], off offset:1024
	v_mov_b32_e32 v48, s6
	v_lshl_add_u64 v[0:1], v[28:29], 0, v[48:49]
	v_lshl_add_u64 v[2:3], v[30:31], 0, v[48:49]
	global_load_ushort v38, v[0:1], off
	global_load_ushort v46, v[2:3], off
	v_mov_b32_e32 v48, s18
	v_lshl_add_u64 v[0:1], v[28:29], 0, v[48:49]
	v_lshl_add_u64 v[2:3], v[30:31], 0, v[48:49]
	global_load_ushort v39, v[0:1], off offset:3072
	global_load_ushort v47, v[2:3], off offset:3072
	s_add_u32 s45, s36, s48
	s_addc_u32 s46, s38, s49
	s_add_u32 s42, s45, s44
	s_addc_u32 s43, s46, 0
	s_add_i32 s39, s39, s33
	v_lshl_add_u64 v[28:29], s[42:43], 0, v[22:23]
	v_lshl_add_u64 v[30:31], s[42:43], 0, v[24:25]
	s_waitcnt vmcnt(0)
	v_lshl_or_b32 v0, v33, 16, v32
	v_lshl_or_b32 v1, v35, 16, v34
	v_lshl_or_b32 v2, v37, 16, v36
	v_lshl_or_b32 v3, v39, 16, v38
	v_lshl_or_b32 v4, v41, 16, v40
	v_lshl_or_b32 v5, v43, 16, v42
	v_lshl_or_b32 v6, v45, 16, v44
	v_lshl_or_b32 v7, v47, 16, v46
	s_cmpk_lt_i32 s39, 0x200
	global_store_dwordx4 v[28:29], v[0:3], off
	global_store_dwordx4 v[30:31], v[4:7], off
	s_cbranch_scc1 .LBB0_814

; #define GAS __attribute__((address_space(1)))
; DI void gate_pass(const Frame& F, int layer) {
;     ...
;         for (int j = 0; j < 3; ++j) {
;             const int idx = i0 + j * stride;
;             if (idx < NIT) {
;                 const int rowid = idx >> 3, cg = idx & 7, bh = rowid / SEQ, t = rowid - bh * SEQ, b = bh / 6, h = bh - 6 * b;
;                 const bf16* src = P + ((size_t)b * SEQ + t) * NP + PC_Z + h * 128 + 16 * cg;
;                 const float* gp = F.in[18] + layer * 128 + 16 * cg;
;                 z[j][0] = *(const GAS v4u*)src; z[j][1] = *(const GAS v4u*)(src + 8);
; #pragma unroll
;                 for (int q = 0; q < 4; ++q) gn[j][q] = *(const GAS f32x4*)(gp + 4 * q);
;             }
;         }
.LBB0_818:
	v_ashrrev_i32_e32 v77, 31, v76
	v_ashrrev_i32_e32 v49, 3, v76
	v_lshrrev_b32_e32 v48, 20, v77
	v_add_u32_e32 v48, v49, v48
	v_ashrrev_i32_e32 v53, 12, v48
	v_and_b32_e32 v48, 0xfffff000, v48
	v_sub_u32_e32 v48, v49, v48
	v_mul_hi_i32 v49, v49, s52
	v_lshrrev_b32_e32 v50, 31, v49
	v_ashrrev_i32_e32 v49, 12, v49
	v_add_u32_e32 v50, v49, v50
	v_ashrrev_i32_e32 v51, 31, v50
	v_mul_i32_i24_e32 v54, -6, v50
	v_lshlrev_b64 v[50:51], 12, v[50:51]
	v_ashrrev_i32_e32 v49, 31, v48
	v_lshl_add_u64 v[48:49], v[50:51], 0, v[48:49]
	v_mov_b64_e32 v[50:51], s[0:1]
	v_mad_u64_u32 v[50:51], s[38:39], v48, s97, v[50:51]
	v_add_lshl_u32 v48, v54, v53, 7
	v_and_b32_e32 v52, 0x70, v78
	v_mad_i32_i24 v51, v49, s97, v51
	v_ashrrev_i32_e32 v49, 31, v48
	v_lshl_add_u64 v[48:49], v[48:49], 1, v[50:51]
	v_lshlrev_b32_e32 v96, 1, v52
	v_lshl_add_u64 v[48:49], v[48:49], 0, v[96:97]
	s_mov_b32 s2, 0x32503000
	v_lshl_add_u64 v[50:51], v[48:49], 0, s[56:57]
	v_add_co_u32_e32 v48, vcc, s2, v48
	v_lshlrev_b32_e32 v68, 2, v52
	s_nop 0
	v_addc_co_u32_e32 v49, vcc, 0, v49, vcc
	global_load_dwordx4 v[64:67], v[48:49], off offset:1536
	global_load_dwordx4 v[52:55], v[50:51], off offset:16
	s_nop 0
	global_load_dwordx4 v[48:51], v68, s[44:45] offset:48
	global_load_dwordx4 v[56:59], v68, s[44:45] offset:32
	global_load_dwordx4 v[60:63], v68, s[44:45] offset:16
	s_nop 0
	global_load_dwordx4 v[68:71], v68, s[44:45]
	v_add_u32_e32 v72, s50, v76
	v_cmp_gt_i32_e64 s[42:43], s53, v72
	v_ashrrev_i32_e32 v73, 31, v72
	s_and_saveexec_b64 s[40:41], s[42:43]
	s_cbranch_execz .LBB0_820
	v_ashrrev_i32_e32 v1, 3, v72
	v_lshrrev_b32_e32 v0, 20, v73
	v_add_u32_e32 v0, v1, v0
	v_ashrrev_i32_e32 v4, 12, v0
	v_and_b32_e32 v0, 0xfffff000, v0
	v_sub_u32_e32 v0, v1, v0
	v_mul_hi_i32 v1, v1, s52
	v_lshrrev_b32_e32 v2, 31, v1
	v_ashrrev_i32_e32 v1, 12, v1
	v_add_u32_e32 v2, v1, v2
	v_ashrrev_i32_e32 v3, 31, v2
	v_mul_i32_i24_e32 v5, -6, v2
	v_lshlrev_b64 v[2:3], 12, v[2:3]
	v_ashrrev_i32_e32 v1, 31, v0
	v_lshl_add_u64 v[0:1], v[2:3], 0, v[0:1]
	v_mov_b64_e32 v[2:3], s[0:1]
	v_mad_u64_u32 v[2:3], s[38:39], v0, s97, v[2:3]
	v_add_lshl_u32 v0, v5, v4, 7
	v_mad_i32_i24 v3, v1, s97, v3
	v_ashrrev_i32_e32 v1, 31, v0
	v_lshl_add_u64 v[0:1], v[0:1], 1, v[2:3]
	v_lshl_add_u64 v[0:1], v[0:1], 0, v[96:97]
	v_lshl_add_u64 v[2:3], v[0:1], 0, s[56:57]
	v_add_co_u32_e32 v0, vcc, 0x32503000, v0
	v_addc_co_u32_e32 v1, vcc, 0, v1, vcc
	global_load_dwordx4 v[4:7], v[0:1], off offset:1536
	s_nop 0
	global_load_dwordx4 v[0:3], v[2:3], off offset:16
.LBB0_820:
	s_or_b64 exec, exec, s[40:41]
	v_add_u32_e32 v74, s51, v76
	v_cmp_gt_i32_e64 s[40:41], s53, v74
	v_ashrrev_i32_e32 v75, 31, v74
	s_and_saveexec_b64 s[48:49], s[40:41]
	s_cbranch_execz .LBB0_822
	v_ashrrev_i32_e32 v9, 3, v74
	v_lshrrev_b32_e32 v8, 20, v75
	v_add_u32_e32 v8, v9, v8
	v_ashrrev_i32_e32 v12, 12, v8
	v_and_b32_e32 v8, 0xfffff000, v8
	v_sub_u32_e32 v8, v9, v8
	v_mul_hi_i32 v9, v9, s52
	v_lshrrev_b32_e32 v10, 31, v9
	v_ashrrev_i32_e32 v9, 12, v9
	v_add_u32_e32 v10, v9, v10
	v_ashrrev_i32_e32 v11, 31, v10
	v_mul_i32_i24_e32 v13, -6, v10
	v_lshlrev_b64 v[10:11], 12, v[10:11]
	v_ashrrev_i32_e32 v9, 31, v8
	v_lshl_add_u64 v[8:9], v[10:11], 0, v[8:9]
	v_mov_b64_e32 v[10:11], s[0:1]
	v_mad_u64_u32 v[10:11], s[38:39], v8, s97, v[10:11]
	v_add_lshl_u32 v8, v13, v12, 7
	v_mad_i32_i24 v11, v9, s97, v11
	v_ashrrev_i32_e32 v9, 31, v8
	v_lshl_add_u64 v[8:9], v[8:9], 1, v[10:11]
	v_lshl_add_u64 v[8:9], v[8:9], 0, v[96:97]
	v_lshl_add_u64 v[10:11], v[8:9], 0, s[56:57]
	v_add_co_u32_e32 v8, vcc, 0x32503000, v8
	v_addc_co_u32_e32 v9, vcc, 0, v9, vcc
	global_load_dwordx4 v[12:15], v[8:9], off offset:1536
	s_nop 0
	global_load_dwordx4 v[8:11], v[10:11], off offset:16
.LBB0_822:
	s_or_b64 exec, exec, s[48:49]
	s_waitcnt vmcnt(4)
	v_mov_b64_e32 v[20:21], v[48:49]
	v_mov_b64_e32 v[28:29], v[56:57]
	v_mov_b64_e32 v[36:37], v[60:61]
	v_mov_b64_e32 v[44:45], v[68:69]
	v_mov_b64_e32 v[22:23], v[50:51]
	v_mov_b64_e32 v[30:31], v[58:59]
	v_mov_b64_e32 v[38:39], v[62:63]
	v_mov_b64_e32 v[46:47], v[70:71]
	v_mov_b64_e32 v[16:17], v[48:49]
	v_mov_b64_e32 v[24:25], v[56:57]
	v_mov_b64_e32 v[32:33], v[60:61]
	v_mov_b64_e32 v[40:41], v[68:69]
	v_mov_b64_e32 v[18:19], v[50:51]
	v_mov_b64_e32 v[26:27], v[58:59]
	v_mov_b64_e32 v[34:35], v[62:63]
	v_mov_b64_e32 v[42:43], v[70:71]
	s_waitcnt vmcnt(5)
	v_lshlrev_b32_e32 v80, 16, v64
	v_and_b32_e32 v81, 0xffff0000, v64
	v_mul_f32_e32 v64, 0xbfb8aa3b, v80
	v_exp_f32_e32 v64, v64
	v_lshlrev_b64 v[76:77], 5, v[76:77]
	v_lshl_add_u64 v[76:77], s[30:31], 0, v[76:77]
	v_add_f32_e32 v64, 1.0, v64
	v_rcp_f32_e32 v82, v64
	v_mul_f32_e32 v64, 0xbfb8aa3b, v81
	v_exp_f32_e32 v64, v64
	s_nop 0
	v_add_f32_e32 v64, 1.0, v64
	v_rcp_f32_e32 v83, v64
	s_nop 0
	v_pk_mul_f32 v[80:81], v[82:83], v[80:81]
	s_waitcnt vmcnt(0)
; #define GAS __attribute__((address_space(1)))
; DI unsigned pk2(float lo, float hi) { f32x2 v = {lo, hi}; bf16x2_t b = __builtin_convertvector(v, bf16x2_t); return __builtin_bit_cast(unsigned, b); }
; DI float bflo(unsigned w) { return __uint_as_float(w << 16); }
; DI float bfhi(unsigned w) { return __uint_as_float(w & 0xffff0000u); }
; DI float silu(float x) { return x * sigm(x); }
; DI void gate_pass(const Frame& F, int layer) {
;     ...
;                 for (int hlf = 0; hlf < 2; ++hlf) {
;                     const v4u zz = z[j][hlf]; const f32x4 ga = gn[j][2 * hlf], gb = gn[j][2 * hlf + 1];
;                     v4u o;
;                     o.x = pk2(silu(bflo(zz.x)) * ga.x, silu(bfhi(zz.x)) * ga.y); o.y = pk2(silu(bflo(zz.y)) * ga.z, silu(bfhi(zz.y)) * ga.w);
;                     o.z = pk2(silu(bflo(zz.z)) * gb.x, silu(bfhi(zz.z)) * gb.y); o.w = pk2(silu(bflo(zz.w)) * gb.z, silu(bfhi(zz.w)) * gb.w);
;                     *(GAS v4u*)(GZ + (size_t)idx * 16 + 8 * hlf) = o;
	v_pk_mul_f32 v[68:69], v[68:69], v[80:81]
	s_nop 0
	v_cvt_pk_bf16_f32 v64, v68, v69
	v_lshlrev_b32_e32 v68, 16, v65
	v_and_b32_e32 v69, 0xffff0000, v65
	v_mul_f32_e32 v65, 0xbfb8aa3b, v68
	v_exp_f32_e32 v65, v65
	s_nop 0
	v_add_f32_e32 v65, 1.0, v65
	v_rcp_f32_e32 v80, v65
	v_mul_f32_e32 v65, 0xbfb8aa3b, v69
	v_exp_f32_e32 v65, v65
	s_nop 0
	v_add_f32_e32 v65, 1.0, v65
	v_rcp_f32_e32 v81, v65
	s_nop 0
	v_pk_mul_f32 v[68:69], v[80:81], v[68:69]
	s_nop 0
	v_pk_mul_f32 v[68:69], v[70:71], v[68:69]
	s_nop 0
	v_cvt_pk_bf16_f32 v65, v68, v69
	v_lshlrev_b32_e32 v68, 16, v66
	v_and_b32_e32 v69, 0xffff0000, v66
	v_mul_f32_e32 v66, 0xbfb8aa3b, v68
	v_exp_f32_e32 v66, v66
	s_nop 0
	v_add_f32_e32 v66, 1.0, v66
	v_rcp_f32_e32 v70, v66
	v_mul_f32_e32 v66, 0xbfb8aa3b, v69
	v_exp_f32_e32 v66, v66
	s_nop 0
	v_add_f32_e32 v66, 1.0, v66
	v_rcp_f32_e32 v71, v66
	s_nop 0
	v_pk_mul_f32 v[68:69], v[70:71], v[68:69]
	s_nop 0
	v_pk_mul_f32 v[60:61], v[60:61], v[68:69]
	s_nop 0
	v_cvt_pk_bf16_f32 v66, v60, v61
	v_lshlrev_b32_e32 v60, 16, v67
	v_and_b32_e32 v61, 0xffff0000, v67
	v_mul_f32_e32 v67, 0xbfb8aa3b, v60
	v_exp_f32_e32 v67, v67
	s_nop 0
	v_add_f32_e32 v67, 1.0, v67
	v_rcp_f32_e32 v68, v67
	v_mul_f32_e32 v67, 0xbfb8aa3b, v61
	v_exp_f32_e32 v67, v67
	s_nop 0
	v_add_f32_e32 v67, 1.0, v67
	v_rcp_f32_e32 v69, v67
	s_nop 0
	v_pk_mul_f32 v[60:61], v[68:69], v[60:61]
	s_nop 0
	v_pk_mul_f32 v[60:61], v[62:63], v[60:61]
	s_nop 0
	v_cvt_pk_bf16_f32 v67, v60, v61
	v_lshlrev_b32_e32 v60, 16, v52
	v_and_b32_e32 v61, 0xffff0000, v52
	v_mul_f32_e32 v52, 0xbfb8aa3b, v60
	v_exp_f32_e32 v52, v52
	global_store_dwordx4 v[76:77], v[64:67], off
	v_add_f32_e32 v52, 1.0, v52
	v_rcp_f32_e32 v62, v52
	v_mul_f32_e32 v52, 0xbfb8aa3b, v61
	v_exp_f32_e32 v52, v52
	s_nop 0
	v_add_f32_e32 v52, 1.0, v52
	v_rcp_f32_e32 v63, v52
	s_nop 0
	v_pk_mul_f32 v[60:61], v[62:63], v[60:61]
	s_nop 0
	v_pk_mul_f32 v[56:57], v[56:57], v[60:61]
	s_nop 0
	v_cvt_pk_bf16_f32 v52, v56, v57
	v_lshlrev_b32_e32 v56, 16, v53
	v_and_b32_e32 v57, 0xffff0000, v53
	v_mul_f32_e32 v53, 0xbfb8aa3b, v56
	v_exp_f32_e32 v53, v53
	s_nop 0
	v_add_f32_e32 v53, 1.0, v53
	v_rcp_f32_e32 v60, v53
	v_mul_f32_e32 v53, 0xbfb8aa3b, v57
	v_exp_f32_e32 v53, v53
	s_nop 0
	v_add_f32_e32 v53, 1.0, v53
	v_rcp_f32_e32 v61, v53
	s_nop 0
	v_pk_mul_f32 v[56:57], v[60:61], v[56:57]
	s_nop 0
	v_pk_mul_f32 v[56:57], v[58:59], v[56:57]
	s_nop 0
	v_cvt_pk_bf16_f32 v53, v56, v57
	v_lshlrev_b32_e32 v56, 16, v54
	v_and_b32_e32 v57, 0xffff0000, v54
	v_mul_f32_e32 v54, 0xbfb8aa3b, v56
	v_exp_f32_e32 v54, v54
	s_nop 0
	v_add_f32_e32 v54, 1.0, v54
	v_rcp_f32_e32 v58, v54
	v_mul_f32_e32 v54, 0xbfb8aa3b, v57
	v_exp_f32_e32 v54, v54
	s_nop 0
	v_add_f32_e32 v54, 1.0, v54
	v_rcp_f32_e32 v59, v54
	s_nop 0
	v_pk_mul_f32 v[56:57], v[58:59], v[56:57]
	s_nop 0
	v_pk_mul_f32 v[48:49], v[48:49], v[56:57]
	s_nop 0
	v_cvt_pk_bf16_f32 v54, v48, v49
	v_lshlrev_b32_e32 v48, 16, v55
	v_and_b32_e32 v49, 0xffff0000, v55
	v_mul_f32_e32 v55, 0xbfb8aa3b, v48
	v_exp_f32_e32 v55, v55
	s_nop 0
	v_add_f32_e32 v55, 1.0, v55
	v_rcp_f32_e32 v56, v55
	v_mul_f32_e32 v55, 0xbfb8aa3b, v49
	v_exp_f32_e32 v55, v55
	s_nop 0
	v_add_f32_e32 v55, 1.0, v55
	v_rcp_f32_e32 v57, v55
	s_nop 0
	v_pk_mul_f32 v[48:49], v[56:57], v[48:49]
	s_nop 0
	v_pk_mul_f32 v[48:49], v[50:51], v[48:49]
	s_nop 0
	v_cvt_pk_bf16_f32 v55, v48, v49
	global_store_dwordx4 v[76:77], v[52:55], off offset:16
	s_and_saveexec_b64 s[48:49], s[42:43]
	s_cbranch_execz .LBB0_824
; #define GAS __attribute__((address_space(1)))
; DI unsigned pk2(float lo, float hi) { f32x2 v = {lo, hi}; bf16x2_t b = __builtin_convertvector(v, bf16x2_t); return __builtin_bit_cast(unsigned, b); }
; DI float bflo(unsigned w) { return __uint_as_float(w << 16); }
; DI float bfhi(unsigned w) { return __uint_as_float(w & 0xffff0000u); }
; DI float silu(float x) { return x * sigm(x); }
; DI void gate_pass(const Frame& F, int layer) {
;     ...
;         for (int j = 0; j < 3; ++j) {
;             const int idx = i0 + j * stride;
;             if (idx < NIT) {
; #pragma unroll
;                 for (int hlf = 0; hlf < 2; ++hlf) {
;                     const v4u zz = z[j][hlf]; const f32x4 ga = gn[j][2 * hlf], gb = gn[j][2 * hlf + 1];
;                     v4u o;
;                     o.x = pk2(silu(bflo(zz.x)) * ga.x, silu(bfhi(zz.x)) * ga.y); o.y = pk2(silu(bflo(zz.y)) * ga.z, silu(bfhi(zz.y)) * ga.w);
;                     o.z = pk2(silu(bflo(zz.z)) * gb.x, silu(bfhi(zz.z)) * gb.y); o.w = pk2(silu(bflo(zz.w)) * gb.z, silu(bfhi(zz.w)) * gb.w);
;                     *(GAS v4u*)(GZ + (size_t)idx * 16 + 8 * hlf) = o;
;                 }
	v_lshlrev_b32_e32 v50, 16, v4
	v_and_b32_e32 v51, 0xffff0000, v4
	v_mul_f32_e32 v52, 0xbfb8aa3b, v50
	v_mul_f32_e32 v53, 0xbfb8aa3b, v51
	v_exp_f32_e32 v52, v52
	v_exp_f32_e32 v53, v53
	v_lshlrev_b64 v[48:49], 5, v[72:73]
	v_lshl_add_u64 v[48:49], s[30:31], 0, v[48:49]
	v_add_f32_e32 v52, 1.0, v52
	v_add_f32_e32 v53, 1.0, v53
	v_rcp_f32_e32 v52, v52
	v_rcp_f32_e32 v53, v53
	s_nop 0
	v_pk_mul_f32 v[50:51], v[52:53], v[50:51]
	s_nop 0
	v_pk_mul_f32 v[50:51], v[44:45], v[50:51]
	v_lshlrev_b32_e32 v52, 16, v5
	v_cvt_pk_bf16_f32 v50, v50, v51
	v_mul_f32_e32 v51, 0xbfb8aa3b, v52
	v_exp_f32_e32 v51, v51
	v_and_b32_e32 v53, 0xffff0000, v5
	v_add_f32_e32 v51, 1.0, v51
	v_rcp_f32_e32 v54, v51
	v_mul_f32_e32 v51, 0xbfb8aa3b, v53
	v_exp_f32_e32 v51, v51
	s_nop 0
	v_add_f32_e32 v51, 1.0, v51
	v_rcp_f32_e32 v55, v51
	s_nop 0
	v_pk_mul_f32 v[52:53], v[54:55], v[52:53]
	s_nop 0
	v_pk_mul_f32 v[52:53], v[46:47], v[52:53]
	s_nop 0
	v_cvt_pk_bf16_f32 v51, v52, v53
	v_lshlrev_b32_e32 v52, 16, v6
	v_and_b32_e32 v53, 0xffff0000, v6
	v_mul_f32_e32 v54, 0xbfb8aa3b, v52
	v_mul_f32_e32 v55, 0xbfb8aa3b, v53
	v_exp_f32_e32 v54, v54
	v_exp_f32_e32 v55, v55
	v_add_f32_e32 v54, 1.0, v54
	v_add_f32_e32 v55, 1.0, v55
	v_rcp_f32_e32 v54, v54
	v_rcp_f32_e32 v55, v55
	s_nop 0
	v_pk_mul_f32 v[52:53], v[54:55], v[52:53]
	s_nop 0
	v_pk_mul_f32 v[52:53], v[36:37], v[52:53]
	v_lshlrev_b32_e32 v54, 16, v7
	v_cvt_pk_bf16_f32 v52, v52, v53
	v_mul_f32_e32 v53, 0xbfb8aa3b, v54
	v_exp_f32_e32 v53, v53
	v_and_b32_e32 v55, 0xffff0000, v7
	v_add_f32_e32 v53, 1.0, v53
	v_rcp_f32_e32 v56, v53
	v_mul_f32_e32 v53, 0xbfb8aa3b, v55
	v_exp_f32_e32 v53, v53
	s_nop 0
	v_add_f32_e32 v53, 1.0, v53
	v_rcp_f32_e32 v57, v53
	s_nop 0
	v_pk_mul_f32 v[54:55], v[56:57], v[54:55]
	s_nop 0
	v_pk_mul_f32 v[54:55], v[38:39], v[54:55]
	s_nop 0
	v_cvt_pk_bf16_f32 v53, v54, v55
	global_store_dwordx4 v[48:49], v[50:53], off
	s_nop 1
	v_lshlrev_b32_e32 v50, 16, v0
	v_and_b32_e32 v51, 0xffff0000, v0
	v_mul_f32_e32 v52, 0xbfb8aa3b, v50
	v_mul_f32_e32 v53, 0xbfb8aa3b, v51
	v_exp_f32_e32 v52, v52
	v_exp_f32_e32 v53, v53
	v_add_f32_e32 v52, 1.0, v52
	v_add_f32_e32 v53, 1.0, v53
	v_rcp_f32_e32 v52, v52
	v_rcp_f32_e32 v53, v53
	s_nop 0
	v_pk_mul_f32 v[50:51], v[52:53], v[50:51]
	s_nop 0
	v_pk_mul_f32 v[50:51], v[28:29], v[50:51]
	v_lshlrev_b32_e32 v52, 16, v1
	v_cvt_pk_bf16_f32 v50, v50, v51
	v_mul_f32_e32 v51, 0xbfb8aa3b, v52
	v_exp_f32_e32 v51, v51
	v_and_b32_e32 v53, 0xffff0000, v1
	v_add_f32_e32 v51, 1.0, v51
	v_rcp_f32_e32 v54, v51
	v_mul_f32_e32 v51, 0xbfb8aa3b, v53
	v_exp_f32_e32 v51, v51
	s_nop 0
	v_add_f32_e32 v51, 1.0, v51
	v_rcp_f32_e32 v55, v51
	s_nop 0
	v_pk_mul_f32 v[52:53], v[54:55], v[52:53]
	s_nop 0
	v_pk_mul_f32 v[52:53], v[30:31], v[52:53]
	s_nop 0
	v_cvt_pk_bf16_f32 v51, v52, v53
	v_lshlrev_b32_e32 v52, 16, v2
	v_and_b32_e32 v53, 0xffff0000, v2
	v_mul_f32_e32 v54, 0xbfb8aa3b, v52
	v_mul_f32_e32 v55, 0xbfb8aa3b, v53
	v_exp_f32_e32 v54, v54
	v_exp_f32_e32 v55, v55
	v_add_f32_e32 v54, 1.0, v54
	v_add_f32_e32 v55, 1.0, v55
	v_rcp_f32_e32 v54, v54
	v_rcp_f32_e32 v55, v55
	s_nop 0
	v_pk_mul_f32 v[52:53], v[54:55], v[52:53]
	s_nop 0
	v_pk_mul_f32 v[52:53], v[20:21], v[52:53]
	v_lshlrev_b32_e32 v54, 16, v3
	v_cvt_pk_bf16_f32 v52, v52, v53
	v_mul_f32_e32 v53, 0xbfb8aa3b, v54
	v_exp_f32_e32 v53, v53
	v_and_b32_e32 v55, 0xffff0000, v3
	v_add_f32_e32 v53, 1.0, v53
	v_rcp_f32_e32 v56, v53
	v_mul_f32_e32 v53, 0xbfb8aa3b, v55
	v_exp_f32_e32 v53, v53
	s_nop 0
	v_add_f32_e32 v53, 1.0, v53
	v_rcp_f32_e32 v57, v53
	s_nop 0
	v_pk_mul_f32 v[54:55], v[56:57], v[54:55]
	s_nop 0
	v_pk_mul_f32 v[54:55], v[22:23], v[54:55]
	s_nop 0
	v_cvt_pk_bf16_f32 v53, v54, v55
	global_store_dwordx4 v[48:49], v[50:53], off offset:16
